# v16 + pass2: one static s_setprio 1 for waves 4-7 for the duration of the pass
# speedup vs baseline: 1.0045x; 1.0045x over previous
.LBB0_1326:
	v_readfirstlane_b32 s19, v17
	s_ashr_i32 s20, s18, 6
	s_ashr_i32 s26, s19, 6
	s_cmp_lt_u32 s26, 4
	s_cbranch_scc1 .Lp2_prio_skip
	s_setprio 1
.Lp2_prio_skip:
	s_ashr_i32 s21, s20, 31
	s_lshl_b32 s19, s18, 8
	s_lshl_b64 s[20:21], s[20:21], 12
	s_and_b32 s19, s19, 0xf00
	s_or_b32 s22, s20, s19
	s_mov_b32 s23, s21
	s_waitcnt vmcnt(4)
	v_lshl_add_u64 v[8:9], s[22:23], 0, v[74:75]
	v_mov_b64_e32 v[10:11], s[52:53]
	s_movk_i32 s19, 0x1600
	v_mad_u64_u32 v[10:11], s[22:23], v8, s19, v[10:11]
	v_mad_i32_i24 v11, v9, s19, v11
	s_lshl_b32 s19, s18, 4
	s_and_b32 s54, s19, 0x300
	v_lshl_add_u64 v[8:9], v[10:11], 0, s[54:55]
	v_mov_b32_e32 v87, v16
	v_lshl_add_u64 v[26:27], v[8:9], 0, v[86:87]
	global_load_dwordx4 v[8:11], v[26:27], off offset:1536
	global_load_dwordx4 v[12:15], v[26:27], off offset:2560
	global_load_dwordx4 v[18:21], v[26:27], off offset:3584
	s_waitcnt vmcnt(4)
	v_add_co_u32_e32 v22, vcc, s68, v26
	s_ashr_i32 s19, s18, 31
	s_nop 0
	v_addc_co_u32_e32 v23, vcc, 0, v27, vcc
	global_load_dwordx4 v[22:25], v[22:23], off offset:512
	s_lshl_b64 s[22:23], s[18:19], 15
	s_add_u32 s22, s62, s22
	s_addc_u32 s23, s63, s23
	v_lshl_or_b32 v28, s26, 11, v92
	s_lshl_b32 s27, s26, 4
	v_ashrrev_i32_e32 v29, 31, v28
	v_or_b32_e32 v42, s27, v95
	v_lshl_add_u64 v[28:29], v[28:29], 1, s[22:23]
	v_ashrrev_i32_e32 v43, 31, v42
	global_load_dwordx2 v[38:39], v[28:29], off
	global_load_dwordx2 v[34:35], v[28:29], off offset:512
	global_load_dwordx2 v[36:37], v[28:29], off offset:1024
	global_load_dwordx2 v[40:41], v[28:29], off offset:1536
	global_load_dwordx2 v[44:45], v[28:29], off offset:2048
	global_load_dwordx2 v[48:49], v[28:29], off offset:2560
	global_load_dwordx2 v[52:53], v[28:29], off offset:3072
	global_load_dwordx2 v[56:57], v[28:29], off offset:3584
	v_lshl_add_u64 v[28:29], v[42:43], 2, s[70:71]
	global_load_dword v87, v[28:29], off
	v_add_u32_e32 v28, v76, v80
	s_mov_b32 s19, 0x2d000
	v_lshlrev_b32_e32 v122, 1, v42
	v_and_or_b32 v43, v221, 64, v77
	v_mov_b32_e32 v46, 0xc0
	v_add_u32_e32 v42, 0, v122
	v_lshl_or_b32 v121, v43, 2, v46
	v_add_u32_e32 v46, v42, v98
	s_waitcnt vmcnt(12)
	ds_write_b128 v28, v[8:11]
	v_add_u32_e32 v8, v78, v80
	s_waitcnt vmcnt(11)
	ds_write_b128 v8, v[12:15] offset:17408
	s_waitcnt vmcnt(10)
	ds_write_b128 v8, v[18:21] offset:37888
	s_waitcnt vmcnt(9)
	ds_write_b128 v81, v[22:25] offset:48128
	v_add_co_u32_e32 v18, vcc, s44, v26
	s_nop 1
	v_addc_co_u32_e32 v19, vcc, 0, v27, vcc
	v_add_co_u32_e32 v22, vcc, s19, v26
	v_or_b32_e32 v26, s27, v79
	s_nop 0
	v_addc_co_u32_e32 v23, vcc, 0, v27, vcc
	v_lshlrev_b32_e32 v120, 1, v26
	global_load_dwordx4 v[8:11], v[18:19], off offset:1536
	global_load_dwordx4 v[12:15], v[18:19], off offset:2560
	s_nop 0
	global_load_dwordx4 v[18:21], v[18:19], off offset:3584
	v_add_u32_e32 v28, v97, v120
	global_load_dwordx4 v[22:25], v[22:23], off offset:512
	s_waitcnt lgkmcnt(0)
	s_barrier
	ds_read_b64_tr_b16 v[26:27], v28 offset:17408
	ds_read_b64_tr_b16 v[28:29], v28 offset:18688
	ds_read_u16 v47, v46 offset:17408
	s_waitcnt lgkmcnt(1)
	v_mfma_f32_16x16x32_bf16 v[30:33], v[4:7], v[26:29], 0
	s_waitcnt lgkmcnt(0)
	v_lshlrev_b32_e32 v50, 16, v47
	v_add_u32_e32 v47, v42, v99
	ds_read_u16 v51, v47
	v_mfma_f32_16x16x32_bf16 v[26:29], v[0:3], v[26:29], 0
	s_nop 2
	v_exp_f32_e32 v54, v30
	v_exp_f32_e32 v50, v50
	s_waitcnt lgkmcnt(0)
	v_lshlrev_b32_e32 v51, 16, v51
	v_mul_f32_e32 v51, v54, v51
	ds_bpermute_b32 v43, v121, v29
	v_cvt_pk_bf16_f32 v51, v51, v51
	ds_write_b16 v47, v51
	v_max_f32_e64 v51, -v30, -v30
	v_min_f32_e32 v51, 0x42e60000, v51
	s_waitcnt lgkmcnt(1)
	v_sub_f32_e32 v30, v43, v30
	v_exp_f32_e32 v51, v51
	v_exp_f32_e32 v30, v30
	v_sub_f32_e32 v50, 1.0, v50
	v_mul_f32_e32 v51, v51, v50
	v_mul_f32_e32 v30, v30, v50
	v_cvt_pk_bf16_f32 v51, v51, v51
	ds_write_b16 v47, v51 offset:8704
	v_cvt_pk_bf16_f32 v30, v30, v30
	ds_write_b16 v46, v30 offset:27648
	ds_read_u16 v30, v46 offset:17728
	ds_read_u16 v50, v47 offset:272
	v_exp_f32_e32 v51, v31
	s_waitcnt lgkmcnt(1)
	v_lshlrev_b32_e32 v30, 16, v30
	s_waitcnt lgkmcnt(0)
	v_lshlrev_b32_e32 v50, 16, v50
	v_mul_f32_e32 v50, v51, v50
	v_cvt_pk_bf16_f32 v50, v50, v50
	ds_write_b16 v47, v50 offset:272
	v_max_f32_e64 v50, -v31, -v31
	v_exp_f32_e32 v30, v30
	v_min_f32_e32 v50, 0x42e60000, v50
	v_sub_f32_e32 v31, v43, v31
	v_exp_f32_e32 v50, v50
	v_exp_f32_e32 v31, v31
	v_sub_f32_e32 v30, 1.0, v30
	v_exp_f32_e32 v51, v33
	v_mul_f32_e32 v50, v50, v30
	v_mul_f32_e32 v30, v31, v30
	v_cvt_pk_bf16_f32 v50, v50, v50
	ds_write_b16 v47, v50 offset:8976
	v_cvt_pk_bf16_f32 v30, v30, v30
	ds_write_b16 v46, v30 offset:27968
	ds_read_u16 v30, v46 offset:18048
	ds_read_u16 v31, v47 offset:544
	v_exp_f32_e32 v50, v32
	s_waitcnt lgkmcnt(1)
	v_lshlrev_b32_e32 v30, 16, v30
	s_waitcnt lgkmcnt(0)
	v_lshlrev_b32_e32 v31, 16, v31
	v_mul_f32_e32 v31, v50, v31
	v_cvt_pk_bf16_f32 v31, v31, v31
	ds_write_b16 v47, v31 offset:544
	v_max_f32_e64 v31, -v32, -v32
	v_exp_f32_e32 v30, v30
	v_min_f32_e32 v31, 0x42e60000, v31
	v_exp_f32_e32 v31, v31
	v_sub_f32_e32 v30, 1.0, v30
	v_mul_f32_e32 v31, v31, v30
	v_cvt_pk_bf16_f32 v31, v31, v31
	ds_write_b16 v47, v31 offset:9248
	v_sub_f32_e32 v31, v43, v32
	v_exp_f32_e32 v31, v31
	v_add_u32_e32 v32, v42, v101
	v_mul_f32_e32 v30, v31, v30
	v_cvt_pk_bf16_f32 v30, v30, v30
	ds_write_b16 v46, v30 offset:28288
	v_add_u32_e32 v30, v42, v100
	ds_read_u16 v31, v30 offset:17408
	ds_read_u16 v50, v32
	s_waitcnt lgkmcnt(1)
	v_lshlrev_b32_e32 v31, 16, v31
	s_waitcnt lgkmcnt(0)
	v_lshlrev_b32_e32 v50, 16, v50
	v_mul_f32_e32 v50, v51, v50
	v_cvt_pk_bf16_f32 v50, v50, v50
	ds_write_b16 v32, v50
	v_max_f32_e64 v50, -v33, -v33
	v_exp_f32_e32 v31, v31
	v_min_f32_e32 v50, 0x42e60000, v50
	v_exp_f32_e32 v50, v50
	v_sub_f32_e32 v31, 1.0, v31
	v_mul_f32_e32 v50, v50, v31
	v_cvt_pk_bf16_f32 v50, v50, v50
	ds_write_b16 v32, v50 offset:8704
	v_sub_f32_e32 v32, v43, v33
	v_exp_f32_e32 v32, v32
	s_nop 0
	v_mul_f32_e32 v31, v32, v31
	v_cvt_pk_bf16_f32 v31, v31, v31
	ds_write_b16 v30, v31 offset:27648
	ds_read_u16 v30, v46 offset:22528
	ds_read_u16 v31, v47 offset:4352
	v_exp_f32_e32 v32, v26
	s_waitcnt lgkmcnt(1)
	v_lshlrev_b32_e32 v30, 16, v30
	s_waitcnt lgkmcnt(0)
	v_lshlrev_b32_e32 v31, 16, v31
	v_mul_f32_e32 v31, v32, v31
	v_cvt_pk_bf16_f32 v31, v31, v31
	ds_write_b16 v47, v31 offset:4352
	v_max_f32_e64 v31, -v26, -v26
	v_exp_f32_e32 v30, v30
	v_min_f32_e32 v31, 0x42e60000, v31
	v_sub_f32_e32 v26, v43, v26
	v_exp_f32_e32 v31, v31
	v_exp_f32_e32 v26, v26
	v_sub_f32_e32 v30, 1.0, v30
	v_mul_f32_e32 v31, v31, v30
	v_mul_f32_e32 v26, v26, v30
	v_cvt_pk_bf16_f32 v31, v31, v31
	ds_write_b16 v47, v31 offset:13056
	v_cvt_pk_bf16_f32 v26, v26, v26
	ds_write_b16 v46, v26 offset:32768
	ds_read_u16 v26, v46 offset:22848
	ds_read_u16 v30, v47 offset:4624
	v_exp_f32_e32 v31, v27
	s_waitcnt lgkmcnt(1)
	v_lshlrev_b32_e32 v26, 16, v26
	s_waitcnt lgkmcnt(0)
	v_lshlrev_b32_e32 v30, 16, v30
	v_mul_f32_e32 v30, v31, v30
	v_cvt_pk_bf16_f32 v30, v30, v30
	ds_write_b16 v47, v30 offset:4624
	v_max_f32_e64 v30, -v27, -v27
	v_exp_f32_e32 v26, v26
	v_min_f32_e32 v30, 0x42e60000, v30
	v_sub_f32_e32 v27, v43, v27
	v_exp_f32_e32 v30, v30
	v_exp_f32_e32 v27, v27
	v_sub_f32_e32 v26, 1.0, v26
	v_exp_f32_e32 v31, v29
	v_mul_f32_e32 v30, v30, v26
	v_mul_f32_e32 v26, v27, v26
	v_cvt_pk_bf16_f32 v30, v30, v30
	ds_write_b16 v47, v30 offset:13328
	v_cvt_pk_bf16_f32 v26, v26, v26
	ds_write_b16 v46, v26 offset:33088
	ds_read_u16 v26, v46 offset:23168
	ds_read_u16 v27, v47 offset:4896
	v_exp_f32_e32 v30, v28
	s_waitcnt lgkmcnt(1)
	v_lshlrev_b32_e32 v26, 16, v26
	s_waitcnt lgkmcnt(0)
	v_lshlrev_b32_e32 v27, 16, v27
	v_mul_f32_e32 v27, v30, v27
	v_cvt_pk_bf16_f32 v27, v27, v27
	ds_write_b16 v47, v27 offset:4896
	v_max_f32_e64 v27, -v28, -v28
	v_exp_f32_e32 v26, v26
	v_min_f32_e32 v27, 0x42e60000, v27
	v_exp_f32_e32 v27, v27
	v_sub_f32_e32 v26, 1.0, v26
	v_mul_f32_e32 v27, v27, v26
	v_cvt_pk_bf16_f32 v27, v27, v27
	ds_write_b16 v47, v27 offset:13600
	v_sub_f32_e32 v27, v43, v28
	v_exp_f32_e32 v27, v27
	v_add_u32_e32 v28, v42, v103
	v_mul_f32_e32 v26, v27, v26
	v_cvt_pk_bf16_f32 v26, v26, v26
	ds_write_b16 v46, v26 offset:33408
	v_add_u32_e32 v26, v42, v102
	ds_read_u16 v27, v26 offset:17408
	ds_read_u16 v30, v28
	s_waitcnt lgkmcnt(1)
	v_lshlrev_b32_e32 v27, 16, v27
	s_waitcnt lgkmcnt(0)
	v_lshlrev_b32_e32 v30, 16, v30
	v_mul_f32_e32 v30, v31, v30
	v_cvt_pk_bf16_f32 v30, v30, v30
	ds_write_b16 v28, v30
	v_max_f32_e64 v30, -v29, -v29
	v_exp_f32_e32 v27, v27
	v_min_f32_e32 v30, 0x42e60000, v30
	v_exp_f32_e32 v30, v30
	v_sub_f32_e32 v27, 1.0, v27
	v_mul_f32_e32 v30, v30, v27
	v_cvt_pk_bf16_f32 v30, v30, v30
	ds_write_b16 v28, v30 offset:8704
	v_sub_f32_e32 v28, v43, v29
	v_exp_f32_e32 v28, v28
	s_nop 0
	v_mul_f32_e32 v27, v28, v27
	v_cvt_pk_bf16_f32 v27, v27, v27
	ds_write_b16 v26, v27 offset:27648
	s_and_saveexec_b64 s[22:23], s[0:1]
	s_cbranch_execz .LBB0_1328
	v_exp_f32_e32 v26, v43
	v_or_b32_e32 v27, s27, v77
	v_lshl_add_u32 v27, v27, 2, 0
	ds_write_b32 v27, v26 offset:56832

.LBB0_1353:
	s_setprio 0
	s_add_i32 s2, s42, 2
	v_readlane_b32 s4, v248, 9
	s_cmp_le_i32 s4, s2
	s_cselect_b64 s[0:1], -1, 0
	s_add_i32 s3, s42, 3
	v_readlane_b32 s5, v248, 10
	s_max_i32 s2, s2, s3
	s_cmp_lt_i32 s2, s5
	s_cselect_b64 s[2:3], -1, 0
	s_and_b64 s[0:1], s[2:3], s[0:1]
	s_and_b64 vcc, exec, s[0:1]
	s_cbranch_vccnz .LBB0_1354
	s_getpc_b64 s[98:99]
